# queue pop atomic: result consumed at unit end instead of waited at unit start
# speedup vs baseline: 1.0127x; 1.0006x over previous
.LBB0_331:
	s_sub_i32 s0, s10, 32
	s_mul_hi_i32 s43, s0, 0x55555556
	s_lshr_b32 s1, s43, 31
	s_add_i32 s43, s43, s1
	s_mul_i32 s44, s43, -3
	s_add_i32 s44, s44, s0
	s_cmp_lt_i32 s10, 32
	s_cselect_b64 s[6:7], -1, 0
	s_cmp_eq_u32 s44, 0
	s_cselect_b64 s[0:1], -1, 0
	s_or_b64 s[0:1], s[6:7], s[0:1]
	s_andn2_b64 vcc, exec, s[0:1]
	s_mov_b64 s[0:1], -1
	s_cbranch_vccz .LBB0_346
	v_mov_b32_e32 v84, v236
	s_and_saveexec_b64 s[0:1], s[14:15]
	s_cbranch_execz .LBB0_336
	s_mov_b64 s[30:31], exec
	v_mbcnt_lo_u32_b32 v2, s30, 0
	v_mbcnt_hi_u32_b32 v2, s31, v2
	v_cmp_eq_u32_e32 vcc, 0, v2
	s_and_saveexec_b64 s[28:29], vcc
	s_cbranch_execz .LBB0_335
	s_bcnt1_i32_b64 s30, s[30:31]
	v_mov_b32_e32 v252, s30
	global_atomic_add v252, v207, v252, s[68:69] sc0
.LBB0_335:
	s_or_b64 exec, exec, s[28:29]
.LBB0_336:
	s_or_b64 exec, exec, s[0:1]
	s_lshl_b32 s0, s43, 1
	s_add_i32 s0, s0, s44
	s_add_i32 s0, s0, -1
	s_mul_hi_i32 s1, s0, 0x2aaaaaab
	s_lshr_b32 s28, s1, 31
	s_ashr_i32 s1, s1, 4
	s_add_i32 s1, s1, s28
	s_add_i32 s64, s1, s40
	s_mulk_i32 s1, 0x60
	s_sub_i32 s0, s0, s1
	s_ashr_i32 s52, s0, 5
	s_and_b32 s1, s0, 31
	s_cmp_eq_u32 s52, 1
	s_cselect_b32 s28, 3, 15
	s_cselect_b32 s29, 2, 4
	s_and_b32 s28, s28, s0
	s_cmp_lt_u32 s0, 32
	s_cselect_b32 s0, 0, s29
	s_cselect_b32 s28, 0, s28
	s_lshr_b32 s48, s1, s0
	s_lshl_b32 s0, s64, 6
	s_ashr_i32 s1, s0, 31
	s_lshl_b64 s[30:31], s[0:1], 1
	s_add_u32 s0, s77, s30
	s_addc_u32 s1, s12, s31
	s_add_u32 s53, s60, s30
	s_addc_u32 s54, s61, s31
	s_add_u32 s55, s13, s30
	v_mov_b32_e32 v52, v0
	s_addc_u32 s65, s18, s31
	s_add_i32 s29, s64, 1
	v_readfirstlane_b32 s49, v52
	s_ashr_i32 s46, s49, 6
	v_cvt_f32_i32_e32 v2, s29
	s_lshl_b32 s50, s46, 3
	s_lshl_b32 s44, s52, 1
	s_lshl_b32 s45, s48, 8
	s_ashr_i32 s51, s50, 31
	s_lshl_b32 s29, 1, s44
	s_add_i32 vcc_lo, s45, 0xffffff80
	s_or_b32 s28, s70, s28
	s_lshl_b64 s[50:51], s[50:51], 1
	v_exp_f32_e64 v2, -v2
	v_cvt_f32_u32_e32 v3, s29
	s_add_u32 s50, s53, s50
	s_addc_u32 s51, s54, s51
	v_and_b32_e32 v85, 63, v52
	s_cmp_eq_u32 s48, 0
	s_cselect_b64 s[66:67], -1, 0
	s_sub_i32 s48, s45, 64
	v_or_b32_e32 v206, s45, v85
	s_or_b32 s53, s45, 64
	v_mul_f32_e32 v53, v2, v3
	v_or_b32_e32 v2, vcc_lo, v85
	v_or_b32_e32 v6, s48, v85
	v_lshlrev_b64 v[10:11], s44, v[206:207]
	v_or_b32_e32 v206, s53, v85
	s_or_b32 s54, s45, 0x80
	v_cndmask_b32_e64 v2, v2, 0, s[66:67]
	v_cndmask_b32_e64 v6, v6, 0, s[66:67]
	v_lshlrev_b64 v[14:15], s44, v[206:207]
	v_or_b32_e32 v206, s54, v85
	s_or_b32 vcc_hi, s45, 0xc0
	v_ashrrev_i32_e32 v3, 31, v2
	v_ashrrev_i32_e32 v7, 31, v6
	v_lshlrev_b64 v[18:19], s44, v[206:207]
	v_or_b32_e32 v206, vcc_hi, v85
	s_mov_b32 s29, s71
	v_lshlrev_b64 v[2:3], s44, v[2:3]
	v_lshlrev_b64 v[6:7], s44, v[6:7]
	v_lshlrev_b64 v[22:23], s44, v[206:207]
	v_lshl_add_u64 v[2:3], v[2:3], 0, s[28:29]
	v_lshl_add_u64 v[6:7], v[6:7], 0, s[28:29]
	v_lshl_add_u64 v[10:11], v[10:11], 0, s[28:29]
	v_lshl_add_u64 v[14:15], v[14:15], 0, s[28:29]
	v_lshl_add_u64 v[18:19], v[18:19], 0, s[28:29]
	v_lshl_add_u64 v[22:23], v[22:23], 0, s[28:29]
	v_lshlrev_b64 v[2:3], 11, v[2:3]
	v_lshlrev_b64 v[6:7], 11, v[6:7]
	v_lshlrev_b64 v[10:11], 11, v[10:11]
	v_lshlrev_b64 v[14:15], 11, v[14:15]
	v_lshlrev_b64 v[18:19], 11, v[18:19]
	v_lshlrev_b64 v[22:23], 11, v[22:23]
	v_lshl_add_u64 v[2:3], s[50:51], 0, v[2:3]
	v_lshl_add_u64 v[6:7], s[50:51], 0, v[6:7]
	v_lshl_add_u64 v[10:11], s[50:51], 0, v[10:11]
	v_lshl_add_u64 v[14:15], s[50:51], 0, v[14:15]
	v_lshl_add_u64 v[18:19], s[50:51], 0, v[18:19]
	v_lshl_add_u64 v[22:23], s[50:51], 0, v[22:23]
	s_lshl_b32 s50, s46, 4
	v_bfe_u32 v26, v52, 2, 4
	v_and_or_b32 v48, s50, 48, v26
	s_ashr_i32 s50, s49, 3
	s_andn2_b32 s50, s50, 31
	v_or_b32_e32 v26, vcc_lo, v48
	s_ashr_i32 s51, s50, 31
	v_cndmask_b32_e64 v26, v26, 0, s[66:67]
	s_lshl_b64 s[50:51], s[50:51], 1
	v_lshlrev_b32_e32 v87, 3, v52
	v_ashrrev_i32_e32 v27, 31, v26
	v_or_b32_e32 v30, s48, v48
	s_add_u32 s50, s55, s50
	v_and_b32_e32 v54, 24, v87
	v_lshlrev_b64 v[26:27], s44, v[26:27]
	v_cndmask_b32_e64 v30, v30, 0, s[66:67]
	s_addc_u32 s51, s65, s51
	v_lshlrev_b32_e32 v206, 1, v54
	v_lshl_add_u64 v[26:27], v[26:27], 0, s[28:29]
	v_ashrrev_i32_e32 v31, 31, v30
	v_and_b32_e32 v86, 31, v52
	v_lshl_add_u64 v[46:47], s[50:51], 0, v[206:207]
	v_lshlrev_b64 v[26:27], 11, v[26:27]
	v_lshlrev_b64 v[30:31], s44, v[30:31]
	s_lshl_b32 s48, s46, 5
	global_load_dwordx4 v[2:5], v[2:3], off
	v_lshl_add_u64 v[26:27], v[46:47], 0, v[26:27]
	v_lshl_add_u64 v[30:31], v[30:31], 0, s[28:29]
	v_or_b32_e32 v206, s45, v48
	v_or_b32_e32 v55, s48, v86
	global_load_dwordx4 v[26:29], v[26:27], off
	v_lshlrev_b64 v[30:31], 11, v[30:31]
	v_lshlrev_b64 v[34:35], s44, v[206:207]
	v_or_b32_e32 v206, s53, v48
	v_add_u32_e32 v50, s45, v55
	global_load_dwordx4 v[6:9], v[6:7], off
	v_lshl_add_u64 v[30:31], v[46:47], 0, v[30:31]
	v_lshl_add_u64 v[34:35], v[34:35], 0, s[28:29]
	v_lshlrev_b64 v[38:39], s44, v[206:207]
	v_or_b32_e32 v206, s54, v48
	v_ashrrev_i32_e32 v51, 31, v50
	global_load_dwordx4 v[30:33], v[30:31], off
	v_lshlrev_b64 v[34:35], 11, v[34:35]
	v_lshlrev_b64 v[42:43], s44, v[206:207]
	v_or_b32_e32 v206, vcc_hi, v48
	v_lshlrev_b64 v[50:51], s44, v[50:51]
	global_load_dwordx4 v[10:13], v[10:11], off
	v_lshl_add_u64 v[34:35], v[46:47], 0, v[34:35]
	v_lshl_add_u64 v[38:39], v[38:39], 0, s[28:29]
	v_lshlrev_b64 v[48:49], s44, v[206:207]
	v_lshl_add_u64 v[82:83], v[50:51], 0, s[28:29]
	v_bfe_u32 v88, v52, 5, 1
	global_load_dwordx4 v[34:37], v[34:35], off
	v_lshlrev_b64 v[38:39], 11, v[38:39]
	v_lshl_add_u64 v[42:43], v[42:43], 0, s[28:29]
	v_lshl_add_u64 v[48:49], v[48:49], 0, s[28:29]
	v_lshlrev_b64 v[50:51], 11, v[82:83]
	global_load_dwordx4 v[14:17], v[14:15], off
	v_lshl_add_u64 v[38:39], v[46:47], 0, v[38:39]
	v_lshlrev_b64 v[42:43], 11, v[42:43]
	v_lshlrev_b64 v[48:49], 11, v[48:49]
	v_lshl_add_u64 v[50:51], s[0:1], 0, v[50:51]
	v_lshlrev_b32_e32 v206, 4, v88
	global_load_dwordx4 v[38:41], v[38:39], off
	v_lshl_add_u64 v[42:43], v[46:47], 0, v[42:43]
	v_lshl_add_u64 v[46:47], v[46:47], 0, v[48:49]
	v_lshl_add_u64 v[50:51], v[50:51], 0, v[206:207]
	global_load_dwordx4 v[18:21], v[18:19], off
	s_lshl_b32 s0, s46, 10
	global_load_dwordx4 v[22:25], v[22:23], off
	s_add_i32 s0, s0, 0
	global_load_dwordx4 v[42:45], v[42:43], off
	s_ashr_i32 s51, s49, 7
	global_load_dwordx4 v[46:49], v[46:47], off
	s_nop 0
	global_load_dwordx4 v[66:69], v[50:51], off
	global_load_dwordx4 v[70:73], v[50:51], off offset:32
	global_load_dwordx4 v[74:77], v[50:51], off offset:64
	global_load_dwordx4 v[78:81], v[50:51], off offset:96
	v_lshl_add_u32 v50, v85, 4, s0
	s_and_b32 s0, s49, 0x3fffffc0
	s_lshl_b32 s0, s0, 2
	s_add_i32 s0, s0, 0
	v_add_u32_e32 v51, 0xc000, v50
	s_waitcnt vmcnt(15)
	ds_write_b128 v50, v[2:5]
	s_waitcnt vmcnt(14)
	ds_write_b128 v50, v[26:29] offset:49152
	s_waitcnt vmcnt(13)
	ds_write_b128 v50, v[6:9] offset:8192
	s_waitcnt vmcnt(12)
	ds_write_b128 v50, v[30:33] offset:57344
	s_waitcnt vmcnt(11)
	ds_write_b128 v50, v[10:13] offset:16384
	s_waitcnt vmcnt(10)
	ds_write_b128 v51, v[34:37] offset:16384
	s_waitcnt vmcnt(9)
	ds_write_b128 v50, v[14:17] offset:24576
	s_waitcnt vmcnt(8)
	ds_write_b128 v51, v[38:41] offset:24576
	s_waitcnt vmcnt(7)
	ds_write_b128 v50, v[18:21] offset:32768
	s_waitcnt vmcnt(5)
	ds_write_b128 v51, v[42:45] offset:32768
	ds_write_b128 v50, v[22:25] offset:40960
	s_waitcnt vmcnt(4)
	ds_write_b128 v51, v[46:49] offset:40960
	s_add_i32 s50, s0, 0x18000
	v_lshlrev_b32_e32 v3, 2, v88
	v_lshl_add_u32 v90, v86, 2, s50
	v_add_u32_e32 v89, s50, v206
	v_sub_u32_e32 v3, v55, v3
	s_lshl_b32 s50, s51, 6
	s_add_i32 s49, s51, 2
	v_subrev_u32_e32 v93, s50, v3
	s_lshl_b32 s50, s51, 13
	s_cmp_lg_u32 0, -1
	s_cselect_b32 s51, 0, 0
	s_add_i32 s51, s51, s50
	v_lshlrev_b32_e32 v6, 4, v52
	v_lshlrev_b32_e32 v2, 1, v52
	s_add_i32 s51, s51, 0x10000
	v_lshlrev_b32_e32 v3, 8, v88
	v_and_b32_e32 v6, 0xc0, v6
	v_and_b32_e32 v2, 32, v2
	v_lshlrev_b32_e32 v4, 10, v88
	v_lshlrev_b32_e32 v5, 4, v86
	v_add3_u32 v3, s51, v3, v6
	v_mul_f32_e32 v91, 0x3fb8aa3b, v53
	v_add3_u32 v94, v3, v2, v54
	v_or3_b32 v2, s50, v4, v5
	s_add_i32 s50, 0, 0x4000
	v_mov_b32_e32 v96, 0
	s_mov_b32 s47, 0
	v_mul_f32_e32 v92, 0x42000000, v91
	v_cmp_gt_u32_e64 s[0:1], 32, v85
	v_add_u32_e32 v95, s50, v2
	v_mov_b32_e32 v97, 0xe0ad78ec
	v_mov_b32_e32 v2, 0
	v_mov_b32_e32 v3, v96
	v_mov_b32_e32 v4, v96
	v_mov_b32_e32 v5, v96
	v_mov_b32_e32 v6, v96
	v_mov_b32_e32 v7, v96
	v_mov_b32_e32 v8, v96
	v_mov_b32_e32 v9, v96
	v_mov_b32_e32 v10, v96
	v_mov_b32_e32 v11, v96
	v_mov_b32_e32 v12, v96
	v_mov_b32_e32 v13, v96
	v_mov_b32_e32 v14, v96
	v_mov_b32_e32 v15, v96
	v_mov_b32_e32 v16, v96
	v_mov_b32_e32 v17, v96
	v_mov_b32_e32 v18, v96
	v_mov_b32_e32 v19, v96
	v_mov_b32_e32 v20, v96
	v_mov_b32_e32 v21, v96
	v_mov_b32_e32 v22, v96
	v_mov_b32_e32 v23, v96
	v_mov_b32_e32 v24, v96
	v_mov_b32_e32 v25, v96
	v_mov_b32_e32 v26, v96
	v_mov_b32_e32 v27, v96
	v_mov_b32_e32 v28, v96
	v_mov_b32_e32 v29, v96
	v_mov_b32_e32 v30, v96
	v_mov_b32_e32 v31, v96
	v_mov_b32_e32 v32, v96
	v_mov_b32_e32 v33, v96
	s_waitcnt lgkmcnt(0)
	s_barrier

.LBB0_351:
	s_or_b64 exec, exec, s[6:7]
	s_addk_i32 s0, 0x800
	s_ashr_i32 s1, s0, 31
	s_lshl_b64 s[0:1], s[0:1], 2
	s_add_u32 s0, s8, s0
	v_or_b32_e32 v4, s10, v233
	s_addc_u32 s1, s9, s1
	v_lshlrev_b32_e32 v4, 2, v4
	global_load_dword v4, v4, s[0:1]
	v_and_b32_e32 v5, 64, v231
	v_add_u32_e32 v5, 64, v5
	v_xor_b32_e32 v6, 1, v231
	v_cmp_lt_i32_e32 vcc, v6, v5
	s_ashr_i32 s44, s43, 2
	s_add_i32 s0, s44, 1
	v_cndmask_b32_e32 v6, v231, v6, vcc
	v_lshlrev_b32_e32 v6, 2, v6
	s_waitcnt vmcnt(1)
	ds_bpermute_b32 v7, v6, v2
	v_max_f32_e32 v2, v2, v2
	s_waitcnt lgkmcnt(0)
	v_max_f32_e32 v7, v7, v7
	v_max_f32_e32 v2, v2, v7
	ds_bpermute_b32 v7, v6, v3
	v_max_f32_e32 v3, v3, v3
	s_waitcnt lgkmcnt(0)
	v_max_f32_e32 v7, v7, v7
	v_max_f32_e32 v3, v3, v7
	s_waitcnt vmcnt(0)
	ds_bpermute_b32 v6, v6, v4
	v_max_f32_e32 v4, v4, v4
	s_waitcnt lgkmcnt(0)
	v_max_f32_e32 v6, v6, v6
	v_min_f32_e32 v4, v4, v6
	v_xor_b32_e32 v6, 2, v231
	v_cmp_lt_i32_e32 vcc, v6, v5
	s_nop 1
	v_cndmask_b32_e32 v6, v231, v6, vcc
	v_lshlrev_b32_e32 v6, 2, v6
	ds_bpermute_b32 v7, v6, v2
	s_waitcnt lgkmcnt(0)
	v_max_f32_e32 v7, v7, v7
	v_max_f32_e32 v2, v2, v7
	ds_bpermute_b32 v7, v6, v3
	ds_bpermute_b32 v6, v6, v4
	s_waitcnt lgkmcnt(1)
	v_max_f32_e32 v7, v7, v7
	s_waitcnt lgkmcnt(0)
	v_max_f32_e32 v6, v6, v6
	v_min_f32_e32 v4, v4, v6
	v_xor_b32_e32 v6, 4, v231
	v_cmp_lt_i32_e32 vcc, v6, v5
	v_max_f32_e32 v3, v3, v7
	s_nop 0
	v_cndmask_b32_e32 v6, v231, v6, vcc
	v_lshlrev_b32_e32 v6, 2, v6
	ds_bpermute_b32 v7, v6, v2
	s_waitcnt lgkmcnt(0)
	v_max_f32_e32 v7, v7, v7
	v_max_f32_e32 v2, v2, v7
	ds_bpermute_b32 v7, v6, v3
	ds_bpermute_b32 v6, v6, v4
	s_waitcnt lgkmcnt(1)
	v_max_f32_e32 v7, v7, v7
	s_waitcnt lgkmcnt(0)
	v_max_f32_e32 v6, v6, v6
	v_min_f32_e32 v4, v4, v6
	v_xor_b32_e32 v6, 8, v231
	v_cmp_lt_i32_e32 vcc, v6, v5
	v_max_f32_e32 v3, v3, v7
	s_nop 0
	v_cndmask_b32_e32 v6, v231, v6, vcc
	v_lshlrev_b32_e32 v6, 2, v6
	ds_bpermute_b32 v7, v6, v2
	s_waitcnt lgkmcnt(0)
	v_max_f32_e32 v7, v7, v7
	v_max_f32_e32 v2, v2, v7
	ds_bpermute_b32 v7, v6, v3
	ds_bpermute_b32 v6, v6, v4
	s_waitcnt lgkmcnt(1)
	v_max_f32_e32 v7, v7, v7
	s_waitcnt lgkmcnt(0)
	v_max_f32_e32 v6, v6, v6
	v_min_f32_e32 v4, v4, v6
	v_xor_b32_e32 v6, 16, v231
	v_cmp_lt_i32_e32 vcc, v6, v5
	v_max_f32_e32 v3, v3, v7
	s_nop 0
	v_cndmask_b32_e32 v6, v231, v6, vcc
	v_lshlrev_b32_e32 v6, 2, v6
	ds_bpermute_b32 v7, v6, v2
	s_waitcnt lgkmcnt(0)
	v_max_f32_e32 v7, v7, v7
	v_max_f32_e32 v2, v2, v7
	ds_bpermute_b32 v7, v6, v3
	ds_bpermute_b32 v6, v6, v4
	s_waitcnt lgkmcnt(1)
	v_max_f32_e32 v7, v7, v7
	s_waitcnt lgkmcnt(0)
	v_max_f32_e32 v6, v6, v6
	v_min_f32_e32 v4, v4, v6
	v_xor_b32_e32 v6, 32, v231
	v_cmp_lt_i32_e32 vcc, v6, v5
	v_max_f32_e32 v3, v3, v7
	s_nop 0
	v_cndmask_b32_e32 v5, v231, v6, vcc
	v_lshlrev_b32_e32 v5, 2, v5
	ds_bpermute_b32 v6, v5, v2
	s_waitcnt lgkmcnt(0)
	v_max_f32_e32 v6, v6, v6
	v_max_f32_e32 v6, v2, v6
	ds_bpermute_b32 v2, v5, v3
	s_waitcnt lgkmcnt(0)
	v_max_f32_e32 v2, v2, v2
	v_max_f32_e32 v7, v3, v2
	ds_bpermute_b32 v2, v5, v4
	s_waitcnt lgkmcnt(0)
	v_max_f32_e32 v2, v2, v2
	v_min_f32_e32 v3, v4, v2
	v_cvt_f32_i32_e32 v4, s0
	s_mov_b32 s0, 0xc2fc0000
	v_mul_f32_e32 v2, -2.0, v4
	v_cmp_gt_f32_e32 vcc, s0, v2
	s_and_b64 s[0:1], vcc, exec
	s_cselect_b32 s0, 0xffffffc0, 0
	v_cndmask_b32_e32 v5, 0, v1, vcc
	v_fmac_f32_e32 v5, -2.0, v4
	v_exp_f32_e32 v4, v5
	v_cmp_gt_f32_e32 vcc, s27, v7
	s_lshl_b32 s47, s30, 8
	v_ldexp_f32 v4, v4, s0
	v_mul_f32_e32 v8, 0xbfb8aa3b, v4
	v_mul_f32_e32 v4, 0x4f800000, v7
	v_cndmask_b32_e32 v4, v7, v4, vcc
	v_sqrt_f32_e32 v5, v4
	s_nop 0
	v_add_u32_e32 v7, -1, v5
	v_fma_f32 v9, -v7, v5, v4
	v_cmp_ge_f32_e64 s[0:1], 0, v9
	v_add_u32_e32 v9, 1, v5
	s_nop 0
	v_cndmask_b32_e64 v7, v5, v7, s[0:1]
	v_fma_f32 v5, -v9, v5, v4
	v_cmp_lt_f32_e64 s[0:1], 0, v5
	s_nop 1
	v_cndmask_b32_e64 v5, v7, v9, s[0:1]
	v_mul_f32_e32 v7, 0x37800000, v5
	v_cndmask_b32_e32 v5, v5, v7, vcc
	v_cmp_class_f32_e32 vcc, v4, v234
	s_nop 1
	v_cndmask_b32_e32 v4, v5, v4, vcc
	v_mul_f32_e32 v209, 0x3f8147ae, v4
	v_cmp_gt_f32_e32 vcc, s27, v6
	v_mul_f32_e32 v4, 0x4f800000, v6
	s_nop 0
	v_cndmask_b32_e32 v4, v6, v4, vcc
	v_sqrt_f32_e32 v5, v4
	s_nop 0
	v_add_u32_e32 v6, -1, v5
	v_fma_f32 v7, -v6, v5, v4
	v_cmp_ge_f32_e64 s[0:1], 0, v7
	v_add_u32_e32 v7, 1, v5
	s_nop 0
	v_cndmask_b32_e64 v6, v5, v6, s[0:1]
	v_fma_f32 v5, -v7, v5, v4
	v_cmp_lt_f32_e64 s[0:1], 0, v5
	s_nop 1
	v_cndmask_b32_e64 v5, v6, v7, s[0:1]
	v_mul_f32_e32 v6, 0x37800000, v5
	v_cndmask_b32_e32 v5, v5, v6, vcc
	v_cmp_class_f32_e32 vcc, v4, v234
	s_nop 1
	v_cndmask_b32_e32 v5, v5, v4, vcc
	v_and_b32_e32 v4, 0x7fffffff, v3
	v_pk_mul_f32 v[4:5], v[4:5], v[208:209]
	s_nop 0
	v_sub_f32_e32 v3, v5, v3
	v_add_f32_e32 v3, v4, v3
	v_add_f32_e32 v3, 0x42420000, v3
	v_div_scale_f32 v4, s[0:1], v8, v8, v3
	v_rcp_f32_e32 v5, v4
	s_nop 0
	v_fma_f32 v6, -v4, v5, 1.0
	v_fmac_f32_e32 v5, v6, v5
	v_div_scale_f32 v6, vcc, v3, v8, v3
	v_mul_f32_e32 v7, v6, v5
	v_fma_f32 v9, -v4, v7, v6
	v_fmac_f32_e32 v7, v9, v5
	v_fma_f32 v4, -v4, v7, v6
	v_div_fmas_f32 v4, v4, v5, v7
	v_div_fixup_f32 v3, v4, v8, v3
	v_cvt_f32_u32_e32 v4, s47
	v_add_f32_e32 v3, v4, v3
	v_cmp_lt_f32_e32 vcc, 0, v3
	v_mul_f32_e32 v3, 0x3c800000, v3
	v_cvt_i32_f32_e32 v3, v3
	v_and_b32_e32 v3, -2, v3
	v_min_i32_e32 v3, s10, v3
	v_cndmask_b32_e32 v3, 0, v3, vcc
	s_nop 0
	v_readfirstlane_b32 s0, v3
	s_and_saveexec_b64 s[6:7], s[14:15]
	s_cbranch_execz .LBB0_355
	s_mov_b64 s[30:31], exec
	v_mbcnt_lo_u32_b32 v3, s30, 0
	v_mbcnt_hi_u32_b32 v3, s31, v3
	v_cmp_eq_u32_e32 vcc, 0, v3
	s_and_saveexec_b64 s[28:29], vcc
	s_cbranch_execz .LBB0_354
	s_bcnt1_i32_b64 s1, s[30:31]
	v_mov_b32_e32 v252, s1
	global_atomic_add v252, v207, v252, s[68:69] sc0
.LBB0_354:
	s_or_b64 exec, exec, s[28:29]
.LBB0_355:
	s_or_b64 exec, exec, s[6:7]
	v_mov_b32_e32 v34, v0
	s_lshl_b32 s1, s43, 5
	v_readfirstlane_b32 s48, v34
	s_lshl_b32 s28, s43, 6
	s_ashr_i32 s43, s48, 6
	s_and_b32 s6, s1, 0xffffffc0
	s_lshl_b32 s1, s44, 7
	s_and_b32 s7, s28, 64
	s_lshl_b32 s49, s43, 5
	s_or_b32 s44, s1, s7
	s_or_b32 s1, s70, s47
	s_ashr_i32 s7, s49, 31
	s_add_u32 s30, s1, s49
	s_addc_u32 s31, s71, s7
	s_lshl_b64 s[50:51], s[30:31], 11
	s_add_u32 s1, s36, s50
	s_addc_u32 s29, s37, s51
	s_ashr_i32 s7, s6, 31
	s_lshl_b64 s[50:51], s[6:7], 1
	s_add_u32 s6, s1, s50
	s_addc_u32 s7, s29, s51
	s_ashr_i32 s1, s0, 31
	s_lshl_b64 s[52:53], s[0:1], 16
	s_add_u32 s52, s52, s72
	s_addc_u32 s53, s53, s73
	s_lshl_b64 s[52:53], s[52:53], 1
	s_add_u32 s1, s23, s52
	s_addc_u32 s29, s24, s53
	s_add_u32 s50, s1, s50
	s_addc_u32 s51, s29, s51
	s_add_u32 s1, s33, s52
	s_addc_u32 s29, s76, s53
	s_ashr_i32 s45, s44, 31
	s_lshl_b64 s[44:45], s[44:45], 1
	v_and_b32_e32 v209, 63, v34
	s_add_u32 s44, s1, s44
	s_addc_u32 s45, s29, s45
	v_lshlrev_b32_e32 v206, 11, v209
	s_lshl_b32 s1, s43, 4
	v_bfe_u32 v3, v34, 2, 4
	v_lshl_add_u64 v[4:5], s[50:51], 0, v[206:207]
	s_lshl_b32 s50, s43, 3
	v_and_or_b32 v3, s1, 48, v3
	s_ashr_i32 s51, s50, 31
	v_lshlrev_b32_e32 v206, 11, v3
	s_ashr_i32 s1, s48, 3
	v_lshl_add_u64 v[216:217], s[50:51], 1, v[4:5]
	v_lshl_add_u64 v[4:5], s[44:45], 0, v[206:207]
	s_and_b32 s44, s1, 0xffffffe0
	s_ashr_i32 s45, s44, 31
	s_lshl_b32 s46, s43, 10
	v_lshlrev_b32_e32 v237, 3, v34
	s_cmp_lg_u32 0, -1
	v_and_b32_e32 v240, 24, v237
	s_cselect_b32 s1, 0, 0
	v_and_b32_e32 v238, 31, v34
	v_lshl_add_u64 v[4:5], s[44:45], 1, v[4:5]
	v_lshlrev_b32_e32 v206, 1, v240
	s_add_i32 s29, s46, s1
	s_mov_b32 s1, m0
	s_mov_b32 m0, s29
	s_nop 0
	global_load_lds_dwordx4 v[216:217], off
	s_mov_b32 m0, s1
	v_bfe_u32 v239, v34, 5, 1
	v_lshl_add_u64 v[218:219], v[4:5], 0, v[206:207]
	s_add_i32 s44, s29, 0x6000
	s_mov_b32 s1, m0
	s_mov_b32 m0, s44
	s_nop 0
	global_load_lds_dwordx4 v[218:219], off
	s_mov_b32 m0, s1
	v_lshlrev_b32_e32 v3, 11, v238
	v_lshl_add_u64 v[4:5], v[216:217], 0, s[78:79]
	s_add_i32 s1, s29, 0x2000
	s_mov_b32 s45, m0
	s_mov_b32 m0, s1
	s_nop 0
	global_load_lds_dwordx4 v[4:5], off
	s_mov_b32 m0, s45
	v_lshl_or_b32 v3, v239, 4, v3
	global_load_dwordx4 v[150:153], v3, s[6:7]
	global_load_dwordx4 v[142:145], v3, s[6:7] offset:32
	global_load_dwordx4 v[134:137], v3, s[6:7] offset:64
	global_load_dwordx4 v[130:133], v3, s[6:7] offset:96
	v_exp_f32_e32 v2, v2
	v_lshlrev_b32_e32 v245, 2, v239
	v_lshlrev_b32_e32 v4, 10, v239
	v_lshlrev_b32_e32 v5, 4, v238
	v_mul_f32_e32 v212, 0x3fb8aa3b, v2
	v_cvt_f32_ubyte0_e32 v2, v245
	v_mul_f32_e32 v206, v212, v2
	v_fma_f32 v19, v212, v2, v212
	v_fma_f32 v18, 0, v212, v206
	v_pk_fma_f32 v[20:21], v[212:213], s[86:87], v[206:207] op_sel_hi:[0,1,0]
	v_pk_fma_f32 v[22:23], v[212:213], s[88:89], v[206:207] op_sel_hi:[0,1,0]
	v_pk_fma_f32 v[24:25], v[212:213], s[90:91], v[206:207] op_sel_hi:[0,1,0]
	v_pk_fma_f32 v[26:27], v[212:213], s[92:93], v[206:207] op_sel_hi:[0,1,0]
	v_pk_fma_f32 v[28:29], v[212:213], s[94:95], v[206:207] op_sel_hi:[0,1,0]
	v_pk_fma_f32 v[30:31], v[212:213], s[96:97], v[206:207] op_sel_hi:[0,1,0]
	v_pk_fma_f32 v[32:33], v[212:213], s[16:17], v[206:207] op_sel_hi:[0,1,0]
	v_lshl_add_u64 v[2:3], v[216:217], 0, s[62:63]
	s_add_i32 s1, s29, 0x4000
	s_mov_b32 s6, m0
	s_mov_b32 m0, s1
	s_nop 0
	global_load_lds_dwordx4 v[2:3], off
	s_mov_b32 m0, s6
	v_add3_u32 v248, 0, v4, v5
	s_waitcnt vmcnt(3) lgkmcnt(0)
	s_barrier
	ds_read_b128 v[36:39], v248
	s_add_i32 s1, s47, 0x100
	s_lshr_b32 s1, s1, 6
	v_mul_f32_e32 v214, 0x42000000, v212
	s_sub_i32 s45, s1, s0
	s_cmp_gt_i32 s45, 4
	v_or_b32_e32 v246, s49, v238
	s_waitcnt vmcnt(3) lgkmcnt(0)
	v_mfma_f32_32x32x16_bf16 v[2:17], v[36:39], v[150:153], v[18:33]
	ds_read_b128 v[36:39], v248 offset:512
	s_waitcnt lgkmcnt(0)
	v_mfma_f32_32x32x16_bf16 v[18:33], v[36:39], v[150:153], v[18:33]
	ds_read_b128 v[36:39], v248 offset:2048
	s_waitcnt vmcnt(2) lgkmcnt(0)
	v_mfma_f32_32x32x16_bf16 v[2:17], v[36:39], v[142:145], v[2:17]
	ds_read_b128 v[36:39], v248 offset:2560
	s_waitcnt lgkmcnt(0)
	v_mfma_f32_32x32x16_bf16 v[18:33], v[36:39], v[142:145], v[18:33]
	ds_read_b128 v[36:39], v248 offset:4096
	s_waitcnt vmcnt(1) lgkmcnt(0)
	v_mfma_f32_32x32x16_bf16 v[2:17], v[36:39], v[134:137], v[2:17]
	ds_read_b128 v[36:39], v248 offset:4608
	s_waitcnt lgkmcnt(0)
	v_mfma_f32_32x32x16_bf16 v[18:33], v[36:39], v[134:137], v[18:33]
	ds_read_b128 v[36:39], v248 offset:6144
	s_waitcnt vmcnt(0) lgkmcnt(0)
	v_mfma_f32_32x32x16_bf16 v[2:17], v[36:39], v[130:133], v[2:17]
	ds_read_b128 v[36:39], v248 offset:6656
	s_waitcnt lgkmcnt(0)
	v_mfma_f32_32x32x16_bf16 v[18:33], v[36:39], v[130:133], v[18:33]
	s_nop 15
	s_nop 7
	s_nop 11
	v_pk_add_f32 v[32:33], v[214:215], v[32:33] op_sel_hi:[0,1]
	v_pk_add_f32 v[30:31], v[214:215], v[30:31] op_sel_hi:[0,1]
	v_pk_add_f32 v[28:29], v[214:215], v[28:29] op_sel_hi:[0,1]
	v_pk_add_f32 v[26:27], v[214:215], v[26:27] op_sel_hi:[0,1]
	v_pk_add_f32 v[24:25], v[214:215], v[24:25] op_sel_hi:[0,1]
	v_pk_add_f32 v[22:23], v[214:215], v[22:23] op_sel_hi:[0,1]
	v_pk_add_f32 v[20:21], v[214:215], v[20:21] op_sel_hi:[0,1]
	v_pk_add_f32 v[18:19], v[214:215], v[18:19] op_sel_hi:[0,1]
	s_cbranch_scc1 .LBB0_357
	s_lshl_b32 s1, s45, 6
	v_subrev_u32_e32 v35, s1, v245
	v_add_u32_e32 v37, 0x120, v35
	v_add_u32_e32 v36, 0x100, v35
	v_cmp_le_i32_e32 vcc, v37, v246
	s_nop 1
	v_cndmask_b32_e32 v18, v235, v18, vcc
	v_cmp_lt_i32_e32 vcc, v36, v246
	s_nop 1
	v_cndmask_b32_e32 v3, v235, v3, vcc
	v_cmp_le_i32_e32 vcc, v36, v246
	v_add_u32_e32 v36, 0x121, v35
	s_nop 0
	v_cndmask_b32_e32 v2, v235, v2, vcc
	v_cmp_le_i32_e32 vcc, v36, v246
	v_add_u32_e32 v36, 0x102, v35
	s_nop 0
	v_cndmask_b32_e32 v19, v235, v19, vcc
	v_cmp_le_i32_e32 vcc, v36, v246
	v_add_u32_e32 v36, 0x122, v35
	s_nop 0
	v_cndmask_b32_e32 v4, v235, v4, vcc
	v_cmp_le_i32_e32 vcc, v36, v246
	v_add_u32_e32 v36, 0x103, v35
	s_nop 0
	v_cndmask_b32_e32 v20, v235, v20, vcc
	v_cmp_le_i32_e32 vcc, v36, v246
	v_add_u32_e32 v36, 0x123, v35
	s_nop 0
	v_cndmask_b32_e32 v5, v235, v5, vcc
	v_cmp_le_i32_e32 vcc, v36, v246
	v_add_u32_e32 v36, 0x108, v35
	s_nop 0
	v_cndmask_b32_e32 v21, v235, v21, vcc
	v_cmp_le_i32_e32 vcc, v36, v246
	v_add_u32_e32 v36, 0x128, v35
	s_nop 0
	v_cndmask_b32_e32 v6, v235, v6, vcc
	v_cmp_le_i32_e32 vcc, v36, v246
	v_add_u32_e32 v36, 0x109, v35
	s_nop 0
	v_cndmask_b32_e32 v22, v235, v22, vcc
	v_cmp_le_i32_e32 vcc, v36, v246
	v_add_u32_e32 v36, 0x129, v35
	s_nop 0
	v_cndmask_b32_e32 v7, v235, v7, vcc
	v_cmp_le_i32_e32 vcc, v36, v246
	v_add_u32_e32 v36, 0x10a, v35
	s_nop 0
	v_cndmask_b32_e32 v23, v235, v23, vcc
	v_cmp_le_i32_e32 vcc, v36, v246
	v_add_u32_e32 v36, 0x12a, v35
	s_nop 0
	v_cndmask_b32_e32 v8, v235, v8, vcc
	v_cmp_le_i32_e32 vcc, v36, v246
	v_add_u32_e32 v36, 0x10b, v35
	s_nop 0
	v_cndmask_b32_e32 v24, v235, v24, vcc
	v_cmp_le_i32_e32 vcc, v36, v246
	v_add_u32_e32 v36, 0x12b, v35
	s_nop 0
	v_cndmask_b32_e32 v9, v235, v9, vcc
	v_cmp_le_i32_e32 vcc, v36, v246
	v_add_u32_e32 v36, 0x110, v35
	s_nop 0
	v_cndmask_b32_e32 v25, v235, v25, vcc
	v_cmp_le_i32_e32 vcc, v36, v246
	v_add_u32_e32 v36, 0x130, v35
	s_nop 0
	v_cndmask_b32_e32 v10, v235, v10, vcc
	v_cmp_le_i32_e32 vcc, v36, v246
	v_add_u32_e32 v36, 0x111, v35
	s_nop 0
	v_cndmask_b32_e32 v26, v235, v26, vcc
	v_cmp_le_i32_e32 vcc, v36, v246
	v_add_u32_e32 v36, 0x131, v35
	s_nop 0
	v_cndmask_b32_e32 v11, v235, v11, vcc
	v_cmp_le_i32_e32 vcc, v36, v246
	v_add_u32_e32 v36, 0x112, v35
	s_nop 0
	v_cndmask_b32_e32 v27, v235, v27, vcc
	v_cmp_le_i32_e32 vcc, v36, v246
	v_add_u32_e32 v36, 0x132, v35
	s_nop 0
	v_cndmask_b32_e32 v12, v235, v12, vcc
	v_cmp_le_i32_e32 vcc, v36, v246
	v_add_u32_e32 v36, 0x113, v35
	s_nop 0
	v_cndmask_b32_e32 v28, v235, v28, vcc
	v_cmp_le_i32_e32 vcc, v36, v246
	v_add_u32_e32 v36, 0x133, v35
	s_nop 0
	v_cndmask_b32_e32 v13, v235, v13, vcc
	v_cmp_le_i32_e32 vcc, v36, v246
	v_add_u32_e32 v36, 0x118, v35
	s_nop 0
	v_cndmask_b32_e32 v29, v235, v29, vcc
	v_cmp_le_i32_e32 vcc, v36, v246
	v_add_u32_e32 v36, 0x138, v35
	s_nop 0
	v_cndmask_b32_e32 v14, v235, v14, vcc
	v_cmp_le_i32_e32 vcc, v36, v246
	v_add_u32_e32 v36, 0x119, v35
	s_nop 0
	v_cndmask_b32_e32 v30, v235, v30, vcc
	v_cmp_le_i32_e32 vcc, v36, v246
	v_add_u32_e32 v36, 0x139, v35
	s_nop 0
	v_cndmask_b32_e32 v15, v235, v15, vcc
	v_cmp_le_i32_e32 vcc, v36, v246
	v_add_u32_e32 v36, 0x11a, v35
	s_nop 0
	v_cndmask_b32_e32 v31, v235, v31, vcc
	v_cmp_le_i32_e32 vcc, v36, v246
	v_add_u32_e32 v36, 0x13a, v35
	s_nop 0
	v_cndmask_b32_e32 v16, v235, v16, vcc
	v_cmp_le_i32_e32 vcc, v36, v246
	v_add_u32_e32 v36, 0x11b, v35
	v_add_u32_e32 v35, 0x13b, v35
	v_cndmask_b32_e32 v32, v235, v32, vcc
	v_cmp_le_i32_e32 vcc, v36, v246
	s_nop 1
	v_cndmask_b32_e32 v17, v235, v17, vcc
	v_cmp_le_i32_e32 vcc, v35, v246
	s_nop 1
	v_cndmask_b32_e32 v33, v235, v33, vcc

.LBB0_387:
	s_lshl_b32 s6, s39, 2
	s_add_i32 s6, s6, 0
	s_add_i32 s6, s6, 0x22188
	v_mov_b32_e32 v2, s6
	ds_write_b32 v2, v252
	s_branch .LBB0_330

	.amdhsa_kernel _Z6mk_fwd4Args
		.amdhsa_group_segment_fixed_size 0
		.amdhsa_private_segment_fixed_size 0
		.amdhsa_kernarg_size 408
		.amdhsa_user_sgpr_count 2
		.amdhsa_user_sgpr_dispatch_ptr 0
		.amdhsa_user_sgpr_queue_ptr 0
		.amdhsa_user_sgpr_kernarg_segment_ptr 1
		.amdhsa_user_sgpr_dispatch_id 0
		.amdhsa_user_sgpr_kernarg_preload_length 0
		.amdhsa_user_sgpr_kernarg_preload_offset 0
		.amdhsa_user_sgpr_private_segment_size 0
		.amdhsa_uses_dynamic_stack 0
		.amdhsa_enable_private_segment 0
		.amdhsa_system_sgpr_workgroup_id_x 1
		.amdhsa_system_sgpr_workgroup_id_y 0
		.amdhsa_system_sgpr_workgroup_id_z 0
		.amdhsa_system_sgpr_workgroup_info 0
		.amdhsa_system_vgpr_workitem_id 0
		.amdhsa_next_free_vgpr 256
		.amdhsa_next_free_sgpr 100
		.amdhsa_accum_offset 256
		.amdhsa_reserve_vcc 1
		.amdhsa_float_round_mode_32 0
		.amdhsa_float_round_mode_16_64 0
		.amdhsa_float_denorm_mode_32 3
		.amdhsa_float_denorm_mode_16_64 3
		.amdhsa_dx10_clamp 1
		.amdhsa_ieee_mode 1
		.amdhsa_fp16_overflow 0
		.amdhsa_tg_split 0
		.amdhsa_exception_fp_ieee_invalid_op 0
		.amdhsa_exception_fp_denorm_src 0
		.amdhsa_exception_fp_ieee_div_zero 0
		.amdhsa_exception_fp_ieee_overflow 0
		.amdhsa_exception_fp_ieee_underflow 0
		.amdhsa_exception_fp_ieee_inexact 0
		.amdhsa_exception_int_div_zero 0
	.end_amdhsa_kernel

amdhsa.kernels:
  - .agpr_count:     0
    .args:
      - .offset:         0
        .size:           152
        .value_kind:     by_value
      - .offset:         152
        .size:           4
        .value_kind:     hidden_block_count_x
      - .offset:         156
        .size:           4
        .value_kind:     hidden_block_count_y
      - .offset:         160
        .size:           4
        .value_kind:     hidden_block_count_z
      - .offset:         164
        .size:           2
        .value_kind:     hidden_group_size_x
      - .offset:         166
        .size:           2
        .value_kind:     hidden_group_size_y
      - .offset:         168
        .size:           2
        .value_kind:     hidden_group_size_z
      - .offset:         170
        .size:           2
        .value_kind:     hidden_remainder_x
      - .offset:         172
        .size:           2
        .value_kind:     hidden_remainder_y
      - .offset:         174
        .size:           2
        .value_kind:     hidden_remainder_z
      - .offset:         192
        .size:           8
        .value_kind:     hidden_global_offset_x
      - .offset:         200
        .size:           8
        .value_kind:     hidden_global_offset_y
      - .offset:         208
        .size:           8
        .value_kind:     hidden_global_offset_z
      - .offset:         216
        .size:           2
        .value_kind:     hidden_grid_dims
      - .offset:         272
        .size:           4
        .value_kind:     hidden_dynamic_lds_size
    .group_segment_fixed_size: 0
    .kernarg_segment_align: 8
    .kernarg_segment_size: 408
    .language:       OpenCL C
    .language_version:
      - 2
      - 0
    .max_flat_workgroup_size: 512
    .name:           _Z6mk_fwd4Args
    .private_segment_fixed_size: 0
    .sgpr_count:     106
    .sgpr_spill_count: 87
    .symbol:         _Z6mk_fwd4Args.kd
    .uniform_work_group_size: 1
    .uses_dynamic_stack: false
    .vgpr_count:     256
    .vgpr_spill_count: 0
    .wavefront_size: 64
